# P1 K-loop: super-phase 2's six LDS-DMA pieces issued inside the following MFMA block instead of before the barrier
# baseline (speedup 1.0000x reference)
; #define PG8_STAGE(bufoff, gbase, voff) do { _Pragma("unroll") for (int _i = 0; _i < 2; ++_i) \
;         __builtin_amdgcn_global_load_lds((const unsigned*)((const char*)(gbase) + (voff)[_i]), (PG8_LAS unsigned*)(lds + (bufoff) + ldsw + _i * 8192), 16, 0, 0); } while (0)
; #define PG8_LDA(dst, b, h) do { _Pragma("unroll") for (int m = 0; m < 4; ++m) _Pragma("unroll") for (int k = 0; k < 2; ++k) dst[m][k] = *(const PG8_LAS bf16x8*)(lds + PG8_SA(b, h) + aoff + m * 2048 + k * 1024); } while (0)
; #define PG8_LDB(dst, b, h) do { _Pragma("unroll") for (int n = 0; n < 2; ++n) _Pragma("unroll") for (int k = 0; k < 2; ++k) dst[n][k] = *(const PG8_LAS bf16x8*)(lds + PG8_SB(b, h) + boff + n * 2048 + k * 1024); } while (0)
; #define PG8_MMA(ai, bj, At, Bt) do { __builtin_amdgcn_s_setprio(1); _Pragma("unroll") for (int m = 0; m < 4; ++m) _Pragma("unroll") for (int n = 0; n < 2; ++n) _Pragma("unroll") for (int k = 0; k < 2; ++k) \
;         acc[ai][bj][m][n] = __builtin_amdgcn_mfma_f32_16x16x32_bf16(Bt[n][k], At[m][k], acc[ai][bj][m][n], 0, 0, 0); __builtin_amdgcn_s_setprio(0); } while (0)
; #define PG8_WAIT_V(n) asm volatile("s_waitcnt vmcnt(" #n ")" ::: "memory")
; #define PG8_WAIT_L(n) asm volatile("s_waitcnt lgkmcnt(" #n ")" ::: "memory")
; #define PG8_BAR __builtin_amdgcn_s_barrier()
; #define PG8_SCHED __builtin_amdgcn_sched_barrier(0)
; template <class Epi, class Sched, bool ALIGN_EPI = false, bool SP2 = false>
; __device__ __forceinline__ void gemm_phase(PG8_LAS unsigned char* lds, const Gemm g, const Sched& S, const Epi& E, const int wid) {
;     ...
;             PG8_LDB(B0, 0, 0); PG8_LDB(B1, 0, 1); PG8_SCHED; PG8_LDA(At, 0, 0); PG8_STAGE(PG8_SA(1, 1), a1 + hstep, voffA);
;             PG8_WAIT_V(8); PG8_WAIT_L(0); PG8_BAR; PG8_MMA(0, 0, At, B0); PG8_MMA(0, 1, At, B1); PG8_BAR; PG8_SCHED;
;             PG8_LDA(At, 0, 1); PG8_STAGE(PG8_SB(0, 0), b2, voffB); PG8_STAGE(PG8_SB(0, 1), b2 + hstep, voffB); PG8_STAGE(PG8_SA(0, 0), a2, voffA);
;             PG8_WAIT_V(8); PG8_WAIT_L(0); PG8_BAR; PG8_MMA(1, 0, At, B0); PG8_MMA(1, 1, At, B1); PG8_BAR; PG8_SCHED;
.LBB0_277:
	ds_read_b128 v[128:131], v163
	ds_read_b128 v[132:135], v163 offset:1024
	ds_read_b128 v[136:139], v163 offset:2048
	ds_read_b128 v[140:143], v163 offset:3072
	ds_read_b128 v[168:171], v165
	s_nop 0
	ds_read_b128 v[172:175], v165 offset:1024
	ds_read_b128 v[176:179], v165 offset:2048
	ds_read_b128 v[180:183], v165 offset:3072
	s_add_u32 s62, s60, 0xfff00080
	s_addc_u32 s63, s61, -1
	s_cmp_eq_u32 s70, 60
	s_cselect_b32 s67, s53, s63
	s_cselect_b32 s66, s59, s62
	s_cselect_b32 s63, s51, s69
	s_cselect_b32 s62, s65, s68
	v_lshl_add_u64 v[216:217], s[60:61], 0, v[152:153]
	s_add_i32 m0, s76, 0xc000
	ds_read_b128 v[184:187], v167
	ds_read_b128 v[188:191], v167 offset:1024
	ds_read_b128 v[192:195], v167 offset:2048
	ds_read_b128 v[196:199], v167 offset:3072
	ds_read_b128 v[200:203], v167 offset:4096
	ds_read_b128 v[204:207], v167 offset:5120
	ds_read_b128 v[208:211], v167 offset:6144
	ds_read_b128 v[212:215], v167 offset:7168
	global_load_lds_dwordx4 v[216:217], off
	v_lshl_add_u64 v[216:217], s[60:61], 0, v[154:155]
	s_add_i32 m0, s76, 0xe000
	s_nop 0
	global_load_lds_dwordx4 v[216:217], off
	s_waitcnt vmcnt(8)
	s_waitcnt lgkmcnt(0)
	s_barrier
	s_setprio 1
	s_waitcnt lgkmcnt(0)
	v_mfma_f32_16x16x32_bf16 v[124:127], v[128:131], v[184:187], v[124:127]
	v_mfma_f32_16x16x32_bf16 v[120:123], v[136:139], v[184:187], v[120:123]
	v_mfma_f32_16x16x32_bf16 v[108:111], v[128:131], v[192:195], v[108:111]
	v_mfma_f32_16x16x32_bf16 v[104:107], v[136:139], v[192:195], v[104:107]
	v_mfma_f32_16x16x32_bf16 v[92:95], v[128:131], v[200:203], v[92:95]
	v_mfma_f32_16x16x32_bf16 v[88:91], v[136:139], v[200:203], v[88:91]
	v_mfma_f32_16x16x32_bf16 v[76:79], v[128:131], v[208:211], v[76:79]
	v_mfma_f32_16x16x32_bf16 v[72:75], v[136:139], v[208:211], v[72:75]
	v_mfma_f32_16x16x32_bf16 v[124:127], v[132:135], v[188:191], v[124:127]
	v_mfma_f32_16x16x32_bf16 v[120:123], v[140:143], v[188:191], v[120:123]
	v_mfma_f32_16x16x32_bf16 v[108:111], v[132:135], v[196:199], v[108:111]
	v_mfma_f32_16x16x32_bf16 v[104:107], v[140:143], v[196:199], v[104:107]
	v_mfma_f32_16x16x32_bf16 v[92:95], v[132:135], v[204:207], v[92:95]
	v_mfma_f32_16x16x32_bf16 v[88:91], v[140:143], v[204:207], v[88:91]
	v_mfma_f32_16x16x32_bf16 v[76:79], v[132:135], v[212:215], v[76:79]
	v_mfma_f32_16x16x32_bf16 v[72:75], v[140:143], v[212:215], v[72:75]
	s_setprio 0
	s_setprio 1
	v_mfma_f32_16x16x32_bf16 v[116:119], v[168:171], v[184:187], v[116:119]
	v_mfma_f32_16x16x32_bf16 v[112:115], v[176:179], v[184:187], v[112:115]
	v_mfma_f32_16x16x32_bf16 v[100:103], v[168:171], v[192:195], v[100:103]
	v_mfma_f32_16x16x32_bf16 v[96:99], v[176:179], v[192:195], v[96:99]
	v_mfma_f32_16x16x32_bf16 v[84:87], v[168:171], v[200:203], v[84:87]
	v_mfma_f32_16x16x32_bf16 v[80:83], v[176:179], v[200:203], v[80:83]
	v_mfma_f32_16x16x32_bf16 v[68:71], v[168:171], v[208:211], v[68:71]
	v_mfma_f32_16x16x32_bf16 v[64:67], v[176:179], v[208:211], v[64:67]
	v_mfma_f32_16x16x32_bf16 v[116:119], v[172:175], v[188:191], v[116:119]
	v_mfma_f32_16x16x32_bf16 v[112:115], v[180:183], v[188:191], v[112:115]
	v_mfma_f32_16x16x32_bf16 v[100:103], v[172:175], v[196:199], v[100:103]
	v_mfma_f32_16x16x32_bf16 v[96:99], v[180:183], v[196:199], v[96:99]
	v_mfma_f32_16x16x32_bf16 v[84:87], v[172:175], v[204:207], v[84:87]
	v_mfma_f32_16x16x32_bf16 v[80:83], v[180:183], v[204:207], v[80:83]
	v_mfma_f32_16x16x32_bf16 v[68:71], v[172:175], v[212:215], v[68:71]
	v_mfma_f32_16x16x32_bf16 v[64:67], v[180:183], v[212:215], v[64:67]
	s_setprio 0
	s_barrier
	ds_read_b128 v[184:187], v167 offset:16384
	ds_read_b128 v[188:191], v167 offset:17408
	ds_read_b128 v[192:195], v167 offset:18432
	ds_read_b128 v[196:199], v167 offset:19456
	ds_read_b128 v[200:203], v167 offset:20480
	ds_read_b128 v[204:207], v167 offset:21504
	ds_read_b128 v[208:211], v167 offset:22528
	ds_read_b128 v[212:215], v167 offset:23552
	s_waitcnt vmcnt(2)
	s_waitcnt lgkmcnt(0)
	s_barrier
	s_setprio 1
	s_waitcnt lgkmcnt(0)
	v_mfma_f32_16x16x32_bf16 v[60:63], v[128:131], v[184:187], v[60:63]
	v_mfma_f32_16x16x32_bf16 v[56:59], v[136:139], v[184:187], v[56:59]
	v_mfma_f32_16x16x32_bf16 v[44:47], v[128:131], v[192:195], v[44:47]
	v_mfma_f32_16x16x32_bf16 v[40:43], v[136:139], v[192:195], v[40:43]
	s_add_i32 s71, s89, s75
	v_lshl_add_u64 v[216:217], s[62:63], 0, v[146:147]
	s_mov_b32 m0, s71
	s_nop 0
	global_load_lds_dwordx4 v[216:217], off
	v_mfma_f32_16x16x32_bf16 v[28:31], v[128:131], v[200:203], v[28:31]
	v_mfma_f32_16x16x32_bf16 v[24:27], v[136:139], v[200:203], v[24:27]
	v_mfma_f32_16x16x32_bf16 v[12:15], v[128:131], v[208:211], v[12:15]
	v_mfma_f32_16x16x32_bf16 v[8:11], v[136:139], v[208:211], v[8:11]
	v_mfma_f32_16x16x32_bf16 v[60:63], v[132:135], v[188:191], v[60:63]
	s_add_i32 m0, s71, 0x2000
	s_add_u32 s72, s62, 0x100000
	v_lshl_add_u64 v[218:219], s[62:63], 0, v[150:151]
	s_addc_u32 s73, s63, 0
	s_add_i32 s71, s90, s75
	global_load_lds_dwordx4 v[218:219], off
	v_mfma_f32_16x16x32_bf16 v[56:59], v[140:143], v[188:191], v[56:59]
	v_mfma_f32_16x16x32_bf16 v[44:47], v[132:135], v[196:199], v[44:47]
	v_mfma_f32_16x16x32_bf16 v[40:43], v[140:143], v[196:199], v[40:43]
	v_mfma_f32_16x16x32_bf16 v[28:31], v[132:135], v[204:207], v[28:31]
	v_mfma_f32_16x16x32_bf16 v[24:27], v[140:143], v[204:207], v[24:27]
	v_lshl_add_u64 v[220:221], s[72:73], 0, v[146:147]
	s_mov_b32 m0, s71
	v_lshl_add_u64 v[222:223], s[66:67], 0, v[148:149]
	global_load_lds_dwordx4 v[220:221], off
	v_mfma_f32_16x16x32_bf16 v[12:15], v[132:135], v[212:215], v[12:15]
	v_mfma_f32_16x16x32_bf16 v[8:11], v[140:143], v[212:215], v[8:11]
	s_setprio 0
	s_setprio 1
	v_mfma_f32_16x16x32_bf16 v[52:55], v[168:171], v[184:187], v[52:55]
	v_mfma_f32_16x16x32_bf16 v[48:51], v[176:179], v[184:187], v[48:51]
	v_mfma_f32_16x16x32_bf16 v[36:39], v[168:171], v[192:195], v[36:39]
	v_lshl_add_u64 v[220:221], s[72:73], 0, v[150:151]
	s_add_i32 m0, s71, 0x2000
	s_nop 0
	global_load_lds_dwordx4 v[220:221], off
	v_mfma_f32_16x16x32_bf16 v[32:35], v[176:179], v[192:195], v[32:35]
	v_mfma_f32_16x16x32_bf16 v[20:23], v[168:171], v[200:203], v[20:23]
	v_mfma_f32_16x16x32_bf16 v[16:19], v[176:179], v[200:203], v[16:19]
	v_mfma_f32_16x16x32_bf16 v[4:7], v[168:171], v[208:211], v[4:7]
	v_mfma_f32_16x16x32_bf16 v[0:3], v[176:179], v[208:211], v[0:3]
	v_lshl_add_u64 v[220:221], s[66:67], 0, v[144:145]
	s_mov_b32 m0, s76
	s_nop 0
	global_load_lds_dwordx4 v[220:221], off
	v_mfma_f32_16x16x32_bf16 v[52:55], v[172:175], v[188:191], v[52:55]
	v_mfma_f32_16x16x32_bf16 v[48:51], v[180:183], v[188:191], v[48:51]
	v_mfma_f32_16x16x32_bf16 v[36:39], v[172:175], v[196:199], v[36:39]
	v_mfma_f32_16x16x32_bf16 v[32:35], v[180:183], v[196:199], v[32:35]
	v_mfma_f32_16x16x32_bf16 v[20:23], v[172:175], v[204:207], v[20:23]
	s_mov_b32 m0, s77
	s_nop 0
	global_load_lds_dwordx4 v[222:223], off
	v_mfma_f32_16x16x32_bf16 v[16:19], v[180:183], v[204:207], v[16:19]
	v_mfma_f32_16x16x32_bf16 v[4:7], v[172:175], v[212:215], v[4:7]
	v_mfma_f32_16x16x32_bf16 v[0:3], v[180:183], v[212:215], v[0:3]
	s_setprio 0
	s_barrier
; #define PG8_STAGE(bufoff, gbase, voff) do { _Pragma("unroll") for (int _i = 0; _i < 2; ++_i) \
;         __builtin_amdgcn_global_load_lds((const unsigned*)((const char*)(gbase) + (voff)[_i]), (PG8_LAS unsigned*)(lds + (bufoff) + ldsw + _i * 8192), 16, 0, 0); } while (0)
; #define PG8_LDA(dst, b, h) do { _Pragma("unroll") for (int m = 0; m < 4; ++m) _Pragma("unroll") for (int k = 0; k < 2; ++k) dst[m][k] = *(const PG8_LAS bf16x8*)(lds + PG8_SA(b, h) + aoff + m * 2048 + k * 1024); } while (0)
; #define PG8_LDB(dst, b, h) do { _Pragma("unroll") for (int n = 0; n < 2; ++n) _Pragma("unroll") for (int k = 0; k < 2; ++k) dst[n][k] = *(const PG8_LAS bf16x8*)(lds + PG8_SB(b, h) + boff + n * 2048 + k * 1024); } while (0)
; #define PG8_MMA(ai, bj, At, Bt) do { __builtin_amdgcn_s_setprio(1); _Pragma("unroll") for (int m = 0; m < 4; ++m) _Pragma("unroll") for (int n = 0; n < 2; ++n) _Pragma("unroll") for (int k = 0; k < 2; ++k) \
;         acc[ai][bj][m][n] = __builtin_amdgcn_mfma_f32_16x16x32_bf16(Bt[n][k], At[m][k], acc[ai][bj][m][n], 0, 0, 0); __builtin_amdgcn_s_setprio(0); } while (0)
; #define PG8_WAIT_V(n) asm volatile("s_waitcnt vmcnt(" #n ")" ::: "memory")
; #define PG8_WAIT_L(n) asm volatile("s_waitcnt lgkmcnt(" #n ")" ::: "memory")
; #define PG8_BAR __builtin_amdgcn_s_barrier()
; #define PG8_SCHED __builtin_amdgcn_sched_barrier(0)
; template <class Epi, class Sched, bool ALIGN_EPI = false, bool SP2 = false>
; __device__ __forceinline__ void gemm_phase(PG8_LAS unsigned char* lds, const Gemm g, const Sched& S, const Epi& E, const int wid) {
;     ...
;             PG8_LDB(B0, 1, 0); PG8_LDB(B1, 1, 1); PG8_SCHED; PG8_LDA(At, 1, 0); PG8_STAGE(PG8_SA(0, 1), a2 + hstep, voffA);
;             PG8_WAIT_V(8); PG8_WAIT_L(0); PG8_BAR; PG8_MMA(0, 0, At, B0); PG8_MMA(0, 1, At, B1); PG8_BAR; PG8_SCHED;
	s_add_i32 s71, 0, 0x18000
	s_add_i32 s72, 0, 0x1c000
	v_add_u32_e32 v140, s71, v161
	v_add_u32_e32 v160, s72, v161
	ds_read_b128 v[128:131], v140
	ds_read_b128 v[132:135], v140 offset:1024
	ds_read_b128 v[136:139], v140 offset:2048
	ds_read_b128 v[140:143], v140 offset:3072
	ds_read_b128 v[168:171], v160
	ds_read_b128 v[172:175], v160 offset:1024
	ds_read_b128 v[176:179], v160 offset:2048
	ds_read_b128 v[180:183], v160 offset:3072
	s_add_u32 s66, s66, 0x100000
	s_addc_u32 s67, s67, 0
	s_mov_b32 m0, s78
	v_lshl_add_u64 v[224:225], s[66:67], 0, v[144:145]
	ds_read_b128 v[184:187], v167 offset:32768
	ds_read_b128 v[188:191], v167 offset:33792
	ds_read_b128 v[192:195], v167 offset:34816
	ds_read_b128 v[196:199], v167 offset:35840
	ds_read_b128 v[200:203], v167 offset:36864
	ds_read_b128 v[204:207], v167 offset:37888
	ds_read_b128 v[208:211], v167 offset:38912
	ds_read_b128 v[212:215], v167 offset:39936
	global_load_lds_dwordx4 v[224:225], off
	v_lshl_add_u64 v[224:225], s[66:67], 0, v[148:149]
	s_mov_b32 m0, s79
	s_nop 0
	global_load_lds_dwordx4 v[224:225], off
	s_waitcnt vmcnt(8)
	s_waitcnt lgkmcnt(0)
	s_barrier
	s_setprio 1
	s_waitcnt lgkmcnt(0)
	v_mfma_f32_16x16x32_bf16 v[124:127], v[128:131], v[184:187], v[124:127]
	v_mfma_f32_16x16x32_bf16 v[120:123], v[136:139], v[184:187], v[120:123]
	v_mfma_f32_16x16x32_bf16 v[108:111], v[128:131], v[192:195], v[108:111]
	v_mfma_f32_16x16x32_bf16 v[104:107], v[136:139], v[192:195], v[104:107]
	v_mfma_f32_16x16x32_bf16 v[92:95], v[128:131], v[200:203], v[92:95]
	v_mfma_f32_16x16x32_bf16 v[88:91], v[136:139], v[200:203], v[88:91]
	v_mfma_f32_16x16x32_bf16 v[76:79], v[128:131], v[208:211], v[76:79]
	v_mfma_f32_16x16x32_bf16 v[72:75], v[136:139], v[208:211], v[72:75]
	v_mfma_f32_16x16x32_bf16 v[124:127], v[132:135], v[188:191], v[124:127]
	v_mfma_f32_16x16x32_bf16 v[120:123], v[140:143], v[188:191], v[120:123]
	v_mfma_f32_16x16x32_bf16 v[108:111], v[132:135], v[196:199], v[108:111]
	v_mfma_f32_16x16x32_bf16 v[104:107], v[140:143], v[196:199], v[104:107]
	v_mfma_f32_16x16x32_bf16 v[92:95], v[132:135], v[204:207], v[92:95]
	v_mfma_f32_16x16x32_bf16 v[88:91], v[140:143], v[204:207], v[88:91]
	v_mfma_f32_16x16x32_bf16 v[76:79], v[132:135], v[212:215], v[76:79]
	v_mfma_f32_16x16x32_bf16 v[72:75], v[140:143], v[212:215], v[72:75]
	s_setprio 0
	s_setprio 1
	v_mfma_f32_16x16x32_bf16 v[116:119], v[168:171], v[184:187], v[116:119]
	v_mfma_f32_16x16x32_bf16 v[112:115], v[176:179], v[184:187], v[112:115]
	v_mfma_f32_16x16x32_bf16 v[100:103], v[168:171], v[192:195], v[100:103]
	v_mfma_f32_16x16x32_bf16 v[96:99], v[176:179], v[192:195], v[96:99]
	v_mfma_f32_16x16x32_bf16 v[84:87], v[168:171], v[200:203], v[84:87]
	v_mfma_f32_16x16x32_bf16 v[80:83], v[176:179], v[200:203], v[80:83]
	v_mfma_f32_16x16x32_bf16 v[68:71], v[168:171], v[208:211], v[68:71]
	v_mfma_f32_16x16x32_bf16 v[64:67], v[176:179], v[208:211], v[64:67]
	v_mfma_f32_16x16x32_bf16 v[116:119], v[172:175], v[188:191], v[116:119]
	v_mfma_f32_16x16x32_bf16 v[112:115], v[180:183], v[188:191], v[112:115]
	v_mfma_f32_16x16x32_bf16 v[100:103], v[172:175], v[196:199], v[100:103]
	v_mfma_f32_16x16x32_bf16 v[96:99], v[180:183], v[196:199], v[96:99]
	v_mfma_f32_16x16x32_bf16 v[84:87], v[172:175], v[204:207], v[84:87]
	v_mfma_f32_16x16x32_bf16 v[80:83], v[180:183], v[204:207], v[80:83]
	v_mfma_f32_16x16x32_bf16 v[68:71], v[172:175], v[212:215], v[68:71]
	v_mfma_f32_16x16x32_bf16 v[64:67], v[180:183], v[212:215], v[64:67]
	s_setprio 0
	s_barrier
; #define PG8_STAGE(bufoff, gbase, voff) do { _Pragma("unroll") for (int _i = 0; _i < 2; ++_i) \
;         __builtin_amdgcn_global_load_lds((const unsigned*)((const char*)(gbase) + (voff)[_i]), (PG8_LAS unsigned*)(lds + (bufoff) + ldsw + _i * 8192), 16, 0, 0); } while (0)
; #define PG8_LDA(dst, b, h) do { _Pragma("unroll") for (int m = 0; m < 4; ++m) _Pragma("unroll") for (int k = 0; k < 2; ++k) dst[m][k] = *(const PG8_LAS bf16x8*)(lds + PG8_SA(b, h) + aoff + m * 2048 + k * 1024); } while (0)
; #define PG8_MMA(ai, bj, At, Bt) do { __builtin_amdgcn_s_setprio(1); _Pragma("unroll") for (int m = 0; m < 4; ++m) _Pragma("unroll") for (int n = 0; n < 2; ++n) _Pragma("unroll") for (int k = 0; k < 2; ++k) \
;         acc[ai][bj][m][n] = __builtin_amdgcn_mfma_f32_16x16x32_bf16(Bt[n][k], At[m][k], acc[ai][bj][m][n], 0, 0, 0); __builtin_amdgcn_s_setprio(0); } while (0)
; #define PG8_WAIT_V(n) asm volatile("s_waitcnt vmcnt(" #n ")" ::: "memory")
; #define PG8_WAIT_L(n) asm volatile("s_waitcnt lgkmcnt(" #n ")" ::: "memory")
; #define PG8_BAR __builtin_amdgcn_s_barrier()
; #define PG8_SCHED __builtin_amdgcn_sched_barrier(0)
; template <class Epi, class Sched, bool ALIGN_EPI = false, bool SP2 = false>
; __device__ __forceinline__ void gemm_phase(PG8_LAS unsigned char* lds, const Gemm g, const Sched& S, const Epi& E, const int wid) {
;     ...
;         for (int t = 0; t < nt; t += 2) {
;             const bool last = (t == nt - 2);
;     ...
;             PG8_LDA(At, 1, 1); PG8_STAGE(PG8_SB(1, 0), b3, voffB); PG8_STAGE(PG8_SB(1, 1), b3 + hstep, voffB); PG8_STAGE(PG8_SA(1, 0), a3, voffA);
;             PG8_WAIT_V(8); PG8_WAIT_L(0); PG8_BAR; PG8_MMA(1, 0, At, B0); PG8_MMA(1, 1, At, B1); PG8_BAR; PG8_SCHED;
	ds_read_b128 v[184:187], v167 offset:49152
	ds_read_b128 v[188:191], v167 offset:50176
	ds_read_b128 v[192:195], v167 offset:51200
	ds_read_b128 v[196:199], v167 offset:52224
	ds_read_b128 v[200:203], v167 offset:53248
	ds_read_b128 v[204:207], v167 offset:54272
	ds_read_b128 v[208:211], v167 offset:55296
	ds_read_b128 v[212:215], v167 offset:56320
	s_waitcnt vmcnt(2)
	s_waitcnt lgkmcnt(0)
	s_barrier
	s_setprio 1
	s_waitcnt lgkmcnt(0)
	v_mfma_f32_16x16x32_bf16 v[60:63], v[128:131], v[184:187], v[60:63]
	v_mfma_f32_16x16x32_bf16 v[56:59], v[136:139], v[184:187], v[56:59]
	v_mfma_f32_16x16x32_bf16 v[44:47], v[128:131], v[192:195], v[44:47]
	v_mfma_f32_16x16x32_bf16 v[40:43], v[136:139], v[192:195], v[40:43]
	s_add_i32 s66, s71, s75
	v_lshl_add_u64 v[216:217], v[216:217], 0, s[40:41]
	s_mov_b32 m0, s66
	s_nop 0
	global_load_lds_dwordx4 v[216:217], off
	v_mfma_f32_16x16x32_bf16 v[28:31], v[128:131], v[200:203], v[28:31]
	v_mfma_f32_16x16x32_bf16 v[24:27], v[136:139], v[200:203], v[24:27]
	v_mfma_f32_16x16x32_bf16 v[12:15], v[128:131], v[208:211], v[12:15]
	v_mfma_f32_16x16x32_bf16 v[8:11], v[136:139], v[208:211], v[8:11]
	v_mfma_f32_16x16x32_bf16 v[60:63], v[132:135], v[188:191], v[60:63]
	s_add_i32 m0, s66, 0x2000
	s_add_u32 s62, s62, 0x100080
	v_lshl_add_u64 v[216:217], v[218:219], 0, s[40:41]
	s_addc_u32 s63, s63, 0
	s_add_i32 s66, s72, s75
	global_load_lds_dwordx4 v[216:217], off
	v_mfma_f32_16x16x32_bf16 v[56:59], v[140:143], v[188:191], v[56:59]
	v_mfma_f32_16x16x32_bf16 v[44:47], v[132:135], v[196:199], v[44:47]
	v_mfma_f32_16x16x32_bf16 v[40:43], v[140:143], v[196:199], v[40:43]
	v_mfma_f32_16x16x32_bf16 v[28:31], v[132:135], v[204:207], v[28:31]
	v_mfma_f32_16x16x32_bf16 v[24:27], v[140:143], v[204:207], v[24:27]
	v_lshl_add_u64 v[216:217], s[62:63], 0, v[146:147]
	s_mov_b32 m0, s66
	s_nop 0
	global_load_lds_dwordx4 v[216:217], off
	v_mfma_f32_16x16x32_bf16 v[12:15], v[132:135], v[212:215], v[12:15]
	v_mfma_f32_16x16x32_bf16 v[8:11], v[140:143], v[212:215], v[8:11]
	s_setprio 0
	s_setprio 1
	v_mfma_f32_16x16x32_bf16 v[52:55], v[168:171], v[184:187], v[52:55]
	v_mfma_f32_16x16x32_bf16 v[48:51], v[176:179], v[184:187], v[48:51]
	v_mfma_f32_16x16x32_bf16 v[36:39], v[168:171], v[192:195], v[36:39]
	v_lshl_add_u64 v[216:217], s[62:63], 0, v[150:151]
	s_add_i32 m0, s66, 0x2000
	s_nop 0
	global_load_lds_dwordx4 v[216:217], off
	v_mfma_f32_16x16x32_bf16 v[32:35], v[176:179], v[192:195], v[32:35]
	v_mfma_f32_16x16x32_bf16 v[20:23], v[168:171], v[200:203], v[20:23]
	v_mfma_f32_16x16x32_bf16 v[16:19], v[176:179], v[200:203], v[16:19]
	v_mfma_f32_16x16x32_bf16 v[4:7], v[168:171], v[208:211], v[4:7]
	v_mfma_f32_16x16x32_bf16 v[0:3], v[176:179], v[208:211], v[0:3]
	v_lshl_add_u64 v[216:217], v[220:221], 0, s[40:41]
	s_mov_b32 m0, s83
	s_nop 0
	global_load_lds_dwordx4 v[216:217], off
	v_mfma_f32_16x16x32_bf16 v[52:55], v[172:175], v[188:191], v[52:55]
	v_mfma_f32_16x16x32_bf16 v[48:51], v[180:183], v[188:191], v[48:51]
	v_mfma_f32_16x16x32_bf16 v[36:39], v[172:175], v[196:199], v[36:39]
	v_mfma_f32_16x16x32_bf16 v[32:35], v[180:183], v[196:199], v[32:35]
	v_mfma_f32_16x16x32_bf16 v[20:23], v[172:175], v[204:207], v[20:23]
	v_lshl_add_u64 v[216:217], v[222:223], 0, s[40:41]
	s_mov_b32 m0, s84
	s_nop 0
	global_load_lds_dwordx4 v[216:217], off
	v_mfma_f32_16x16x32_bf16 v[16:19], v[180:183], v[204:207], v[16:19]
	v_mfma_f32_16x16x32_bf16 v[4:7], v[172:175], v[212:215], v[4:7]
	v_mfma_f32_16x16x32_bf16 v[0:3], v[180:183], v[212:215], v[0:3]
	s_setprio 0
	s_barrier
	s_add_i32 s70, s70, 2
	s_add_u32 s60, s60, 0x100
	s_addc_u32 s61, s61, 0
	s_add_u32 s68, s68, 0x100
	s_addc_u32 s69, s69, 0
	s_cmp_gt_u32 s70, 61
	s_cbranch_scc0 .LBB0_277
	s_and_b64 vcc, exec, s[42:43]
	s_cbranch_vccz .LBB0_280
	s_barrier
